# P5 LayerNorm phase: ln_g/ln_b read in place from their registers (128 v_mov copies per unit removed, fmac -> fma with the parameter as addend)
# baseline (speedup 1.0000x reference)
; __device__ __forceinline__ float bf2f(short s) { return __uint_as_float(((unsigned)(unsigned short)s) << 16); }
; __device__ __forceinline__ bf16x8 tobf8(f32x8 x) { u32x4 w = {cvtpk(x[0], x[1]), cvtpk(x[2], x[3]), cvtpk(x[4], x[5]), cvtpk(x[6], x[7])}; return *reinterpret_cast<bf16x8*>(&w); }
; __device__ __forceinline__ int v_st(int k, int c) { const int kk = (k & ~0xC) | ((k & 4) << 1) | ((k & 8) >> 1); return ((kk >> 3) * 4 + (c >> 5)) * 512 + ((kk & 7) * 32 + (c & 31)) * 2; }
; __device__ __forceinline__ void spatial_phase(const Params& p, char* lds) {
;     ...
;         for (int q = 0; q < 4; ++q) { const int st_ = q >> 1, ch_ = q & 1; if (samp && st_ == 1) continue;
; #pragma unroll
;             for (int hf = 0; hf < 2; ++hf) { const int k = sr + 32 * hf, s = st_ * 64 + k; const int cc = ch_ * 128 + sc;
;                 bf16x8 w = {};
;                 if (s < nrows) { const float mu = mu_[st_ * 2 + hf], rs = rs_[st_ * 2 + hf];
;                     const bf16x8 rw = raw[q * 2 + hf];
;                     const f32x4 g0 = *(const f32x4*)(p.ln_g + g * GD + cc), g1 = *(const f32x4*)(p.ln_g + g * GD + cc + 4), b0 = *(const f32x4*)(p.ln_b + g * GD + cc), b1 = *(const f32x4*)(p.ln_b + g * GD + cc + 4);
;                     f32x8 y;
; #pragma unroll
;                     for (int i = 0; i < 4; ++i) { y[i] = (bf2f(rw[i]) - mu) * rs * g0[i] + b0[i]; y[4 + i] = (bf2f(rw[4 + i]) - mu) * rs * g1[i] + b1[i]; }
;                     if (samp) { float* d = p.out + O_SGV + (size_t)(cidx * TS + s) * CW + g * GD + cc; __builtin_nontemporal_store((f32x4){y[0], y[1], y[2], y[3]}, (f32x4*)d); __builtin_nontemporal_store((f32x4){y[4], y[5], y[6], y[7]}, (f32x4*)(d + 4)); }
;                     w = tobf8(y); }
;                 *(bf16x8*)(lds + q * 16384 + v_st(k, sc)) = w; } }
.LBB0_1211:
	s_xor_b64 s[70:71], s[40:41], -1
	s_addk_i32 s58, 0xfc00
	s_and_b64 s[40:41], s[68:69], exec
	s_cselect_b32 s59, 16, 0x80
	v_cndmask_b32_e64 v0, 0, 1, s[68:69]
	s_lshl_b32 s80, s42, 8
	v_cmp_gt_u32_e64 s[42:43], s59, v180
	v_mov_b32_e32 v3, 0
	v_cmp_ne_u32_e64 s[40:41], 1, v0
	v_mov_b32_e32 v2, 0
	v_mov_b32_e32 v1, 0
	v_mov_b32_e32 v0, 0
	s_and_saveexec_b64 s[44:45], s[42:43]
	s_cbranch_execz .LBB0_1215
	s_lshl_b32 s74, s80, 2
	v_lshl_add_u64 v[0:1], v[220:221], 0, s[74:75]
	v_lshl_add_u64 v[12:13], v[222:223], 0, s[74:75]
	s_nop 0
	s_nop 0
	s_nop 0
	v_and_b32_e32 v17, 0xffff0000, v64
	v_lshlrev_b32_e32 v16, 16, v64
	v_pk_add_f32 v[16:17], v[16:17], v[186:187] op_sel_hi:[1,0] neg_lo:[0,1] neg_hi:[0,1]
	s_and_b64 vcc, exec, s[40:41]
	v_pk_mul_f32 v[16:17], v[16:17], v[98:99] op_sel_hi:[1,0]
	s_nop 0
	v_pk_fma_f32 v[0:1], v[16:17], v[32:33], v[40:41]
	v_and_b32_e32 v13, 0xffff0000, v66
	v_lshlrev_b32_e32 v12, 16, v66
	v_pk_add_f32 v[12:13], v[12:13], v[186:187] op_sel_hi:[1,0] neg_lo:[0,1] neg_hi:[0,1]
	s_nop 0
	v_pk_mul_f32 v[12:13], v[12:13], v[98:99] op_sel_hi:[1,0]
	s_nop 0
	v_pk_fma_f32 v[4:5], v[12:13], v[36:37], v[44:45]
	v_and_b32_e32 v9, 0xffff0000, v65
	v_lshlrev_b32_e32 v8, 16, v65
	v_pk_add_f32 v[8:9], v[8:9], v[186:187] op_sel_hi:[1,0] neg_lo:[0,1] neg_hi:[0,1]
	s_nop 0
	v_pk_mul_f32 v[8:9], v[8:9], v[98:99] op_sel_hi:[1,0]
	s_nop 0
	v_pk_fma_f32 v[2:3], v[8:9], v[34:35], v[42:43]
	v_and_b32_e32 v9, 0xffff0000, v67
	v_lshlrev_b32_e32 v8, 16, v67
	v_pk_add_f32 v[8:9], v[8:9], v[186:187] op_sel_hi:[1,0] neg_lo:[0,1] neg_hi:[0,1]
	s_nop 0
	v_pk_mul_f32 v[8:9], v[8:9], v[98:99] op_sel_hi:[1,0]
	s_nop 0
	v_pk_fma_f32 v[6:7], v[8:9], v[38:39], v[46:47]
	s_cbranch_vccnz .LBB0_1214
	v_add_u32_e32 v8, s58, v180
	v_ashrrev_i32_e32 v9, 31, v8
	v_lshlrev_b64 v[8:9], 14, v[8:9]
	v_lshl_add_u64 v[8:9], s[62:63], 0, v[8:9]
	v_lshl_add_u64 v[8:9], v[8:9], 0, s[74:75]
	v_lshlrev_b32_e32 v10, 2, v182
	v_mov_b32_e32 v11, v96
	v_lshl_add_u64 v[8:9], v[8:9], 0, v[10:11]
	global_store_dwordx4 v[8:9], v[0:3], off nt
	global_store_dwordx4 v[8:9], v[4:7], off offset:16 nt

; __device__ __forceinline__ float bf2f(short s) { return __uint_as_float(((unsigned)(unsigned short)s) << 16); }
; __device__ __forceinline__ bf16x8 tobf8(f32x8 x) { u32x4 w = {cvtpk(x[0], x[1]), cvtpk(x[2], x[3]), cvtpk(x[4], x[5]), cvtpk(x[6], x[7])}; return *reinterpret_cast<bf16x8*>(&w); }
; __device__ __forceinline__ int v_st(int k, int c) { const int kk = (k & ~0xC) | ((k & 4) << 1) | ((k & 8) >> 1); return ((kk >> 3) * 4 + (c >> 5)) * 512 + ((kk & 7) * 32 + (c & 31)) * 2; }
; __device__ __forceinline__ void spatial_phase(const Params& p, char* lds) {
;     ...
;         for (int q = 0; q < 4; ++q) { const int st_ = q >> 1, ch_ = q & 1; if (samp && st_ == 1) continue;
; #pragma unroll
;             for (int hf = 0; hf < 2; ++hf) { const int k = sr + 32 * hf, s = st_ * 64 + k; const int cc = ch_ * 128 + sc;
;                 bf16x8 w = {};
;                 if (s < nrows) { const float mu = mu_[st_ * 2 + hf], rs = rs_[st_ * 2 + hf];
;                     const bf16x8 rw = raw[q * 2 + hf];
;                     const f32x4 g0 = *(const f32x4*)(p.ln_g + g * GD + cc), g1 = *(const f32x4*)(p.ln_g + g * GD + cc + 4), b0 = *(const f32x4*)(p.ln_b + g * GD + cc), b1 = *(const f32x4*)(p.ln_b + g * GD + cc + 4);
;                     f32x8 y;
; #pragma unroll
;                     for (int i = 0; i < 4; ++i) { y[i] = (bf2f(rw[i]) - mu) * rs * g0[i] + b0[i]; y[4 + i] = (bf2f(rw[4 + i]) - mu) * rs * g1[i] + b1[i]; }
;                     if (samp) { float* d = p.out + O_SGV + (size_t)(cidx * TS + s) * CW + g * GD + cc; __builtin_nontemporal_store((f32x4){y[0], y[1], y[2], y[3]}, (f32x4*)d); __builtin_nontemporal_store((f32x4){y[4], y[5], y[6], y[7]}, (f32x4*)(d + 4)); }
;                     w = tobf8(y); }
;                 *(bf16x8*)(lds + q * 16384 + v_st(k, sc)) = w; } }
.LBB0_1215:
	s_or_b64 exec, exec, s[44:45]
	ds_write_b128 v234, v[0:3]
	v_cmp_gt_u32_e64 s[44:45], s59, v200
	v_mov_b32_e32 v3, 0
	v_mov_b32_e32 v2, 0
	v_mov_b32_e32 v1, 0
	v_mov_b32_e32 v0, 0
	s_and_saveexec_b64 s[72:73], s[44:45]
	s_cbranch_execz .LBB0_1219
	s_lshl_b32 s74, s80, 2
	v_lshl_add_u64 v[0:1], v[220:221], 0, s[74:75]
	v_lshl_add_u64 v[12:13], v[222:223], 0, s[74:75]
	s_nop 0
	s_nop 0
	s_nop 0
	v_and_b32_e32 v17, 0xffff0000, v68
	v_lshlrev_b32_e32 v16, 16, v68
	v_pk_add_f32 v[16:17], v[16:17], v[184:185] op_sel_hi:[1,0] neg_lo:[0,1] neg_hi:[0,1]
	s_and_b64 vcc, exec, s[40:41]
	v_pk_mul_f32 v[16:17], v[16:17], v[194:195] op_sel_hi:[1,0]
	s_nop 0
	v_pk_fma_f32 v[0:1], v[16:17], v[32:33], v[40:41]
	v_and_b32_e32 v13, 0xffff0000, v70
	v_lshlrev_b32_e32 v12, 16, v70
	v_pk_add_f32 v[12:13], v[12:13], v[184:185] op_sel_hi:[1,0] neg_lo:[0,1] neg_hi:[0,1]
	s_nop 0
	v_pk_mul_f32 v[12:13], v[12:13], v[194:195] op_sel_hi:[1,0]
	s_nop 0
	v_pk_fma_f32 v[4:5], v[12:13], v[36:37], v[44:45]
	v_and_b32_e32 v9, 0xffff0000, v69
	v_lshlrev_b32_e32 v8, 16, v69
	v_pk_add_f32 v[8:9], v[8:9], v[184:185] op_sel_hi:[1,0] neg_lo:[0,1] neg_hi:[0,1]
	s_nop 0
	v_pk_mul_f32 v[8:9], v[8:9], v[194:195] op_sel_hi:[1,0]
	s_nop 0
	v_pk_fma_f32 v[2:3], v[8:9], v[34:35], v[42:43]
	v_and_b32_e32 v9, 0xffff0000, v71
	v_lshlrev_b32_e32 v8, 16, v71
	v_pk_add_f32 v[8:9], v[8:9], v[184:185] op_sel_hi:[1,0] neg_lo:[0,1] neg_hi:[0,1]
	s_nop 0
	v_pk_mul_f32 v[8:9], v[8:9], v[194:195] op_sel_hi:[1,0]
	s_nop 0
	v_pk_fma_f32 v[6:7], v[8:9], v[38:39], v[46:47]
	s_cbranch_vccnz .LBB0_1218
	v_add_u32_e32 v8, s58, v200
	v_ashrrev_i32_e32 v9, 31, v8
	v_lshlrev_b64 v[8:9], 14, v[8:9]
	v_lshl_add_u64 v[8:9], s[62:63], 0, v[8:9]
	v_lshl_add_u64 v[8:9], v[8:9], 0, s[74:75]
	v_lshlrev_b32_e32 v10, 2, v182
	v_mov_b32_e32 v11, v96
	v_lshl_add_u64 v[8:9], v[8:9], 0, v[10:11]
	global_store_dwordx4 v[8:9], v[0:3], off nt
	global_store_dwordx4 v[8:9], v[4:7], off offset:16 nt

; __device__ __forceinline__ float bf2f(short s) { return __uint_as_float(((unsigned)(unsigned short)s) << 16); }
; __device__ __forceinline__ bf16x8 tobf8(f32x8 x) { u32x4 w = {cvtpk(x[0], x[1]), cvtpk(x[2], x[3]), cvtpk(x[4], x[5]), cvtpk(x[6], x[7])}; return *reinterpret_cast<bf16x8*>(&w); }
; __device__ __forceinline__ int v_st(int k, int c) { const int kk = (k & ~0xC) | ((k & 4) << 1) | ((k & 8) >> 1); return ((kk >> 3) * 4 + (c >> 5)) * 512 + ((kk & 7) * 32 + (c & 31)) * 2; }
; __device__ __forceinline__ void spatial_phase(const Params& p, char* lds) {
;     ...
;         for (int q = 0; q < 4; ++q) { const int st_ = q >> 1, ch_ = q & 1; if (samp && st_ == 1) continue;
; #pragma unroll
;             for (int hf = 0; hf < 2; ++hf) { const int k = sr + 32 * hf, s = st_ * 64 + k; const int cc = ch_ * 128 + sc;
;                 bf16x8 w = {};
;                 if (s < nrows) { const float mu = mu_[st_ * 2 + hf], rs = rs_[st_ * 2 + hf];
;                     const bf16x8 rw = raw[q * 2 + hf];
;                     const f32x4 g0 = *(const f32x4*)(p.ln_g + g * GD + cc), g1 = *(const f32x4*)(p.ln_g + g * GD + cc + 4), b0 = *(const f32x4*)(p.ln_b + g * GD + cc), b1 = *(const f32x4*)(p.ln_b + g * GD + cc + 4);
;                     f32x8 y;
; #pragma unroll
;                     for (int i = 0; i < 4; ++i) { y[i] = (bf2f(rw[i]) - mu) * rs * g0[i] + b0[i]; y[4 + i] = (bf2f(rw[4 + i]) - mu) * rs * g1[i] + b1[i]; }
;                     if (samp) { float* d = p.out + O_SGV + (size_t)(cidx * TS + s) * CW + g * GD + cc; __builtin_nontemporal_store((f32x4){y[0], y[1], y[2], y[3]}, (f32x4*)d); __builtin_nontemporal_store((f32x4){y[4], y[5], y[6], y[7]}, (f32x4*)(d + 4)); }
;                     w = tobf8(y); }
;                 *(bf16x8*)(lds + q * 16384 + v_st(k, sc)) = w; } }
.LBB0_1219:
	s_or_b64 exec, exec, s[72:73]
	ds_write_b128 v235, v[0:3]
	v_mov_b32_e32 v3, 0
	v_mov_b32_e32 v2, 0
	v_mov_b32_e32 v1, 0
	v_mov_b32_e32 v0, 0
	s_and_saveexec_b64 s[72:73], s[42:43]
	s_cbranch_execz .LBB0_1223
	s_lshl_b32 s74, s80, 2
	v_lshl_add_u64 v[0:1], v[220:221], 0, s[74:75]
	v_lshl_add_u64 v[12:13], v[222:223], 0, s[74:75]
	s_nop 0
	s_nop 0
	s_nop 0
	v_and_b32_e32 v17, 0xffff0000, v72
	v_lshlrev_b32_e32 v16, 16, v72
	v_pk_add_f32 v[16:17], v[16:17], v[186:187] op_sel_hi:[1,0] neg_lo:[0,1] neg_hi:[0,1]
	s_and_b64 vcc, exec, s[40:41]
	v_pk_mul_f32 v[16:17], v[16:17], v[98:99] op_sel_hi:[1,0]
	s_nop 0
	v_pk_fma_f32 v[0:1], v[16:17], v[48:49], v[56:57]
	v_and_b32_e32 v13, 0xffff0000, v74
	v_lshlrev_b32_e32 v12, 16, v74
	v_pk_add_f32 v[12:13], v[12:13], v[186:187] op_sel_hi:[1,0] neg_lo:[0,1] neg_hi:[0,1]
	s_nop 0
	v_pk_mul_f32 v[12:13], v[12:13], v[98:99] op_sel_hi:[1,0]
	s_nop 0
	v_pk_fma_f32 v[4:5], v[12:13], v[52:53], v[60:61]
	v_and_b32_e32 v9, 0xffff0000, v73
	v_lshlrev_b32_e32 v8, 16, v73
	v_pk_add_f32 v[8:9], v[8:9], v[186:187] op_sel_hi:[1,0] neg_lo:[0,1] neg_hi:[0,1]
	s_nop 0
	v_pk_mul_f32 v[8:9], v[8:9], v[98:99] op_sel_hi:[1,0]
	s_nop 0
	v_pk_fma_f32 v[2:3], v[8:9], v[50:51], v[58:59]
	v_and_b32_e32 v9, 0xffff0000, v75
	v_lshlrev_b32_e32 v8, 16, v75
	v_pk_add_f32 v[8:9], v[8:9], v[186:187] op_sel_hi:[1,0] neg_lo:[0,1] neg_hi:[0,1]
	s_nop 0
	v_pk_mul_f32 v[8:9], v[8:9], v[98:99] op_sel_hi:[1,0]
	s_nop 0
	v_pk_fma_f32 v[6:7], v[8:9], v[54:55], v[62:63]
	s_cbranch_vccnz .LBB0_1222
	v_add_u32_e32 v8, s58, v180
	v_ashrrev_i32_e32 v9, 31, v8
	v_lshlrev_b64 v[8:9], 14, v[8:9]
	v_lshl_add_u64 v[8:9], s[62:63], 0, v[8:9]
	v_lshl_add_u64 v[8:9], v[8:9], 0, s[74:75]
	v_lshlrev_b32_e32 v10, 2, v182
	v_mov_b32_e32 v11, v96
	v_lshl_add_u64 v[8:9], v[8:9], 0, v[10:11]
	global_store_dwordx4 v[8:9], v[0:3], off offset:512 nt
	global_store_dwordx4 v[8:9], v[4:7], off offset:528 nt

; __device__ __forceinline__ float bf2f(short s) { return __uint_as_float(((unsigned)(unsigned short)s) << 16); }
; __device__ __forceinline__ bf16x8 tobf8(f32x8 x) { u32x4 w = {cvtpk(x[0], x[1]), cvtpk(x[2], x[3]), cvtpk(x[4], x[5]), cvtpk(x[6], x[7])}; return *reinterpret_cast<bf16x8*>(&w); }
; __device__ __forceinline__ int v_st(int k, int c) { const int kk = (k & ~0xC) | ((k & 4) << 1) | ((k & 8) >> 1); return ((kk >> 3) * 4 + (c >> 5)) * 512 + ((kk & 7) * 32 + (c & 31)) * 2; }
; __device__ __forceinline__ void spatial_phase(const Params& p, char* lds) {
;     ...
;         for (int q = 0; q < 4; ++q) { const int st_ = q >> 1, ch_ = q & 1; if (samp && st_ == 1) continue;
; #pragma unroll
;             for (int hf = 0; hf < 2; ++hf) { const int k = sr + 32 * hf, s = st_ * 64 + k; const int cc = ch_ * 128 + sc;
;                 bf16x8 w = {};
;                 if (s < nrows) { const float mu = mu_[st_ * 2 + hf], rs = rs_[st_ * 2 + hf];
;                     const bf16x8 rw = raw[q * 2 + hf];
;                     const f32x4 g0 = *(const f32x4*)(p.ln_g + g * GD + cc), g1 = *(const f32x4*)(p.ln_g + g * GD + cc + 4), b0 = *(const f32x4*)(p.ln_b + g * GD + cc), b1 = *(const f32x4*)(p.ln_b + g * GD + cc + 4);
;                     f32x8 y;
; #pragma unroll
;                     for (int i = 0; i < 4; ++i) { y[i] = (bf2f(rw[i]) - mu) * rs * g0[i] + b0[i]; y[4 + i] = (bf2f(rw[4 + i]) - mu) * rs * g1[i] + b1[i]; }
;                     if (samp) { float* d = p.out + O_SGV + (size_t)(cidx * TS + s) * CW + g * GD + cc; __builtin_nontemporal_store((f32x4){y[0], y[1], y[2], y[3]}, (f32x4*)d); __builtin_nontemporal_store((f32x4){y[4], y[5], y[6], y[7]}, (f32x4*)(d + 4)); }
;                     w = tobf8(y); }
;                 *(bf16x8*)(lds + q * 16384 + v_st(k, sc)) = w; } }
.LBB0_1223:
	s_or_b64 exec, exec, s[72:73]
	ds_write_b128 v234, v[0:3] offset:16384
	v_mov_b32_e32 v3, 0
	v_mov_b32_e32 v2, 0
	v_mov_b32_e32 v1, 0
	v_mov_b32_e32 v0, 0
	s_and_saveexec_b64 s[42:43], s[44:45]
	s_cbranch_execz .LBB0_1227
	s_lshl_b32 s74, s80, 2
	v_lshl_add_u64 v[0:1], v[220:221], 0, s[74:75]
	v_lshl_add_u64 v[12:13], v[222:223], 0, s[74:75]
	s_nop 0
	s_nop 0
	s_nop 0
	v_and_b32_e32 v17, 0xffff0000, v76
	v_lshlrev_b32_e32 v16, 16, v76
	v_pk_add_f32 v[16:17], v[16:17], v[184:185] op_sel_hi:[1,0] neg_lo:[0,1] neg_hi:[0,1]
	s_and_b64 vcc, exec, s[40:41]
	v_pk_mul_f32 v[16:17], v[16:17], v[194:195] op_sel_hi:[1,0]
	s_nop 0
	v_pk_fma_f32 v[0:1], v[16:17], v[48:49], v[56:57]
	v_and_b32_e32 v13, 0xffff0000, v78
	v_lshlrev_b32_e32 v12, 16, v78
	v_pk_add_f32 v[12:13], v[12:13], v[184:185] op_sel_hi:[1,0] neg_lo:[0,1] neg_hi:[0,1]
	s_nop 0
	v_pk_mul_f32 v[12:13], v[12:13], v[194:195] op_sel_hi:[1,0]
	s_nop 0
	v_pk_fma_f32 v[4:5], v[12:13], v[52:53], v[60:61]
	v_and_b32_e32 v9, 0xffff0000, v77
	v_lshlrev_b32_e32 v8, 16, v77
	v_pk_add_f32 v[8:9], v[8:9], v[184:185] op_sel_hi:[1,0] neg_lo:[0,1] neg_hi:[0,1]
	s_nop 0
	v_pk_mul_f32 v[8:9], v[8:9], v[194:195] op_sel_hi:[1,0]
	s_nop 0
	v_pk_fma_f32 v[2:3], v[8:9], v[50:51], v[58:59]
	v_and_b32_e32 v9, 0xffff0000, v79
	v_lshlrev_b32_e32 v8, 16, v79
	v_pk_add_f32 v[8:9], v[8:9], v[184:185] op_sel_hi:[1,0] neg_lo:[0,1] neg_hi:[0,1]
	s_nop 0
	v_pk_mul_f32 v[8:9], v[8:9], v[194:195] op_sel_hi:[1,0]
	s_nop 0
	v_pk_fma_f32 v[6:7], v[8:9], v[54:55], v[62:63]
	s_cbranch_vccnz .LBB0_1226
	v_add_u32_e32 v8, s58, v200
	v_ashrrev_i32_e32 v9, 31, v8
	v_lshlrev_b64 v[8:9], 14, v[8:9]
	v_lshl_add_u64 v[8:9], s[62:63], 0, v[8:9]
	v_lshl_add_u64 v[8:9], v[8:9], 0, s[74:75]
	v_lshlrev_b32_e32 v10, 2, v182
	v_mov_b32_e32 v11, v96
	v_lshl_add_u64 v[8:9], v[8:9], 0, v[10:11]
	global_store_dwordx4 v[8:9], v[0:3], off offset:512 nt
	global_store_dwordx4 v[8:9], v[4:7], off offset:528 nt

; __device__ __forceinline__ float bf2f(short s) { return __uint_as_float(((unsigned)(unsigned short)s) << 16); }
; __device__ __forceinline__ bf16x8 tobf8(f32x8 x) { u32x4 w = {cvtpk(x[0], x[1]), cvtpk(x[2], x[3]), cvtpk(x[4], x[5]), cvtpk(x[6], x[7])}; return *reinterpret_cast<bf16x8*>(&w); }
; __device__ __forceinline__ int v_st(int k, int c) { const int kk = (k & ~0xC) | ((k & 4) << 1) | ((k & 8) >> 1); return ((kk >> 3) * 4 + (c >> 5)) * 512 + ((kk & 7) * 32 + (c & 31)) * 2; }
; __device__ __forceinline__ void spatial_phase(const Params& p, char* lds) {
;     ...
;         for (int q = 0; q < 4; ++q) { const int st_ = q >> 1, ch_ = q & 1; if (samp && st_ == 1) continue;
; #pragma unroll
;             for (int hf = 0; hf < 2; ++hf) { const int k = sr + 32 * hf, s = st_ * 64 + k; const int cc = ch_ * 128 + sc;
;                 bf16x8 w = {};
;                 if (s < nrows) { const float mu = mu_[st_ * 2 + hf], rs = rs_[st_ * 2 + hf];
;                     const bf16x8 rw = raw[q * 2 + hf];
;                     const f32x4 g0 = *(const f32x4*)(p.ln_g + g * GD + cc), g1 = *(const f32x4*)(p.ln_g + g * GD + cc + 4), b0 = *(const f32x4*)(p.ln_b + g * GD + cc), b1 = *(const f32x4*)(p.ln_b + g * GD + cc + 4);
;                     f32x8 y;
; #pragma unroll
;                     for (int i = 0; i < 4; ++i) { y[i] = (bf2f(rw[i]) - mu) * rs * g0[i] + b0[i]; y[4 + i] = (bf2f(rw[4 + i]) - mu) * rs * g1[i] + b1[i]; }
;                     if (samp) { float* d = p.out + O_SGV + (size_t)(cidx * TS + s) * CW + g * GD + cc; __builtin_nontemporal_store((f32x4){y[0], y[1], y[2], y[3]}, (f32x4*)d); __builtin_nontemporal_store((f32x4){y[4], y[5], y[6], y[7]}, (f32x4*)(d + 4)); }
;                     w = tobf8(y); }
;                 *(bf16x8*)(lds + q * 16384 + v_st(k, sc)) = w; } }
.LBB0_1227:
	s_or_b64 exec, exec, s[42:43]
	s_and_b64 vcc, exec, s[38:39]
	ds_write_b128 v235, v[0:3] offset:16384
	s_cbranch_vccnz .LBB0_1233
	s_lshl_b32 s74, s80, 2
	v_lshl_add_u64 v[8:9], v[222:223], 0, s[74:75]
	v_lshl_add_u64 v[6:7], v[220:221], 0, s[74:75]
	v_and_b32_e32 v5, 0xffff0000, v80
	v_sub_f32_e32 v5, v5, v197
	v_mul_f32_e32 v5, v5, v99
	v_lshlrev_b32_e32 v4, 16, v80
	v_sub_f32_e32 v4, v4, v197
	v_mul_f32_e32 v4, v4, v99
	v_fma_f32 v5, v5, v33, v41
	v_and_b32_e32 v11, 0xffff0000, v81
	v_sub_f32_e32 v11, v11, v197
	v_mul_f32_e32 v11, v11, v99
	v_fma_f32 v13, v11, v35, v43
	v_lshlrev_b32_e32 v11, 16, v82
	v_sub_f32_e32 v11, v11, v197
	v_mul_f32_e32 v11, v11, v99
	v_fma_f32 v4, v4, v32, v40
	v_lshlrev_b32_e32 v10, 16, v81
	v_fma_f32 v11, v11, v36, v44
	v_and_b32_e32 v0, 0xffff0000, v82
	v_sub_f32_e32 v10, v10, v197
	v_sub_f32_e32 v0, v0, v197
	v_mul_f32_e32 v10, v10, v99
	v_mul_f32_e32 v0, v0, v99
	v_fma_f32 v10, v10, v34, v42
	v_fma_f32 v12, v0, v37, v45
	v_lshlrev_b32_e32 v0, 16, v83
	v_sub_f32_e32 v0, v0, v197
	v_mul_f32_e32 v0, v0, v99
	v_fma_f32 v14, v0, v38, v46
	v_and_b32_e32 v0, 0xffff0000, v83
	v_sub_f32_e32 v0, v0, v197
	v_mul_f32_e32 v0, v0, v99
	v_fma_f32 v3, v0, v39, v47
	v_cvt_pk_bf16_f32 v0, v4, v5
	v_cvt_pk_bf16_f32 v1, v10, v13
	v_cvt_pk_bf16_f32 v2, v11, v12
	v_cvt_pk_bf16_f32 v3, v14, v3
	ds_write_b128 v234, v[0:3] offset:32768
	v_mov_b32_e32 v0, 0
	v_mov_b32_e32 v2, 0
	v_mov_b32_e32 v3, 0
	v_mov_b32_e32 v4, 0
	v_mov_b32_e32 v5, 0
	s_and_saveexec_b64 s[40:41], s[36:37]
	s_cbranch_execz .LBB0_1230
	v_lshlrev_b32_e32 v1, 16, v84
	v_sub_f32_e32 v1, v1, v199
	v_mul_f32_e32 v1, v1, v97
	v_fma_f32 v1, v1, v32, v40
	v_and_b32_e32 v10, 0xffff0000, v84
	v_sub_f32_e32 v10, v10, v199
	v_mul_f32_e32 v10, v10, v97
	v_fma_f32 v10, v10, v33, v41
	v_lshlrev_b32_e32 v11, 16, v85
	v_sub_f32_e32 v11, v11, v199
	v_mul_f32_e32 v11, v11, v97
	v_fma_f32 v11, v11, v34, v42
	v_and_b32_e32 v12, 0xffff0000, v85
	v_sub_f32_e32 v12, v12, v199
	v_mul_f32_e32 v12, v12, v97
	v_fma_f32 v13, v12, v35, v43
	v_lshlrev_b32_e32 v12, 16, v86
	v_sub_f32_e32 v12, v12, v199
	v_mul_f32_e32 v12, v12, v97
	v_fma_f32 v12, v12, v36, v44
	v_and_b32_e32 v2, 0xffff0000, v86
	v_sub_f32_e32 v2, v2, v199
	v_mul_f32_e32 v2, v2, v97
	v_fma_f32 v14, v2, v37, v45
	v_lshlrev_b32_e32 v2, 16, v87
	v_sub_f32_e32 v2, v2, v199
	v_mul_f32_e32 v2, v2, v97
	v_fma_f32 v15, v2, v38, v46
	v_and_b32_e32 v2, 0xffff0000, v87
	v_sub_f32_e32 v2, v2, v199
	v_mul_f32_e32 v2, v2, v97
	v_fma_f32 v5, v2, v39, v47
	v_cvt_pk_bf16_f32 v2, v1, v10
	v_cvt_pk_bf16_f32 v3, v11, v13
	v_cvt_pk_bf16_f32 v4, v12, v14
	v_cvt_pk_bf16_f32 v5, v15, v5
.LBB0_1230:
	s_or_b64 exec, exec, s[40:41]
	ds_write_b128 v235, v[2:5] offset:32768
	v_lshlrev_b32_e32 v1, 16, v88
	v_sub_f32_e32 v1, v1, v197
	v_mul_f32_e32 v1, v1, v99
	v_fma_f32 v1, v1, v48, v56
	v_and_b32_e32 v10, 0xffff0000, v88
	v_sub_f32_e32 v10, v10, v197
	v_mul_f32_e32 v10, v10, v99
	v_fma_f32 v10, v10, v49, v57
	v_lshlrev_b32_e32 v11, 16, v89
	v_sub_f32_e32 v11, v11, v197
	v_mul_f32_e32 v11, v11, v99
	v_fma_f32 v11, v11, v50, v58
	v_and_b32_e32 v12, 0xffff0000, v89
	v_sub_f32_e32 v12, v12, v197
	v_mul_f32_e32 v12, v12, v99
	v_fma_f32 v13, v12, v51, v59
	v_lshlrev_b32_e32 v12, 16, v90
	v_sub_f32_e32 v12, v12, v197
	v_mul_f32_e32 v12, v12, v99
	v_fma_f32 v12, v12, v52, v60
	v_and_b32_e32 v2, 0xffff0000, v90
	v_sub_f32_e32 v2, v2, v197
	v_mul_f32_e32 v2, v2, v99
	v_fma_f32 v14, v2, v53, v61
	v_lshlrev_b32_e32 v2, 16, v91
	v_sub_f32_e32 v2, v2, v197
	v_mul_f32_e32 v2, v2, v99
	v_fma_f32 v15, v2, v54, v62
	v_and_b32_e32 v2, 0xffff0000, v91
	v_sub_f32_e32 v2, v2, v197
	v_mul_f32_e32 v2, v2, v99
	v_fma_f32 v5, v2, v55, v63
	v_cvt_pk_bf16_f32 v2, v1, v10
	v_cvt_pk_bf16_f32 v3, v11, v13
	v_cvt_pk_bf16_f32 v4, v12, v14
	v_cvt_pk_bf16_f32 v5, v15, v5
	ds_write_b128 v234, v[2:5] offset:49152
	v_mov_b32_e32 v1, 0
	v_mov_b32_e32 v2, 0
	v_mov_b32_e32 v3, 0
	s_and_saveexec_b64 s[40:41], s[36:37]
	s_cbranch_execz .LBB0_1232
	s_nop 0
	s_nop 0
	s_nop 0
	v_and_b32_e32 v16, 0xffff0000, v95
	v_sub_f32_e32 v16, v16, v199
	v_mul_f32_e32 v16, v16, v97
	v_fma_f32 v7, v16, v55, v63
	v_lshlrev_b32_e32 v11, 16, v95
	v_sub_f32_e32 v11, v11, v199
	v_mul_f32_e32 v11, v11, v97
	v_fma_f32 v6, v11, v54, v62
	v_and_b32_e32 v10, 0xffff0000, v94
	v_sub_f32_e32 v10, v10, v199
	v_mul_f32_e32 v10, v10, v97
	v_fma_f32 v5, v10, v53, v61
	v_lshlrev_b32_e32 v9, 16, v94
	v_sub_f32_e32 v9, v9, v199
	v_mul_f32_e32 v9, v9, v97
	v_fma_f32 v8, v9, v52, v60
	v_and_b32_e32 v4, 0xffff0000, v93
	v_sub_f32_e32 v4, v4, v199
	v_mul_f32_e32 v4, v4, v97
	v_fma_f32 v3, v4, v51, v59
	v_lshlrev_b32_e32 v4, 16, v93
	v_sub_f32_e32 v4, v4, v199
	v_mul_f32_e32 v4, v4, v97
	v_fma_f32 v2, v4, v50, v58
	v_and_b32_e32 v4, 0xffff0000, v92
	v_sub_f32_e32 v4, v4, v199
	v_mul_f32_e32 v4, v4, v97
	v_fma_f32 v1, v4, v49, v57
	v_lshlrev_b32_e32 v4, 16, v92
	v_sub_f32_e32 v4, v4, v199
	v_mul_f32_e32 v4, v4, v97
	v_fma_f32 v0, v4, v48, v56
	v_cvt_pk_bf16_f32 v0, v0, v1
	v_cvt_pk_bf16_f32 v1, v2, v3
	v_cvt_pk_bf16_f32 v2, v8, v5
	v_cvt_pk_bf16_f32 v3, v6, v7
